# as previous version plus a tile variant without the constant-shift subtraction when the shift is zero and the tile is not the masked last one (staging of next K/V tile kept ahead of the body)
# speedup vs baseline: 1.0132x; 1.0132x over previous
; #define LAS __attribute__((address_space(3)))
; #define SBAR() __builtin_amdgcn_sched_barrier(0)
; __device__ __forceinline__ void qkt(f32x16& p0, f32x16& p1, LAS const unsigned char* Ks, const bf16x8* qr, LAS const unsigned char* qt, int r32, int hi) {
;     p0 = (f32x16){}; p1 = (f32x16){};
; #pragma unroll
;     for (int d0 = 0; d0 < 12; ++d0) { const int cb = (d0 * 16 + hi * 8) * 2;
;         const bf16x8 b0 = *(const LAS bf16x8*)(Ks + KSWZ(r32, cb));
;         const bf16x8 b1 = *(const LAS bf16x8*)(Ks + KSWZ(32 + r32, cb));
;         const bf16x8 qf = d0 < QREG ? qr[d0 < QREG ? d0 : 0] : *(const LAS bf16x8*)(qt + (d0 - QREG) * 1024);
;         p0 = __builtin_amdgcn_mfma_f32_32x32x16_bf16(b0, qf, p0, 0, 0, 0);
;         p1 = __builtin_amdgcn_mfma_f32_32x32x16_bf16(b1, qf, p1, 0, 0, 0);
;         if ((d0 & 3) == 3) SBAR(); }
; }
; __device__ __forceinline__ void expP(f32x16& p0, f32x16& p1, float MB) {
; #pragma unroll
;     for (int r = 0; r < 16; ++r) p0[r] = __builtin_amdgcn_exp2f(p0[r] - MB);
; #pragma unroll
;     for (int r = 0; r < 16; ++r) p1[r] = __builtin_amdgcn_exp2f(p1[r] - MB);
; }
; __device__ __forceinline__ void finishP(const f32x16& p0, const f32x16& p1, float& l_reg, bf16x8& pa0, bf16x8& pa1, bf16x8& pa2, bf16x8& pa3) {
;     float ps = 0.f;
; #pragma unroll
;     for (int r = 0; r < 16; ++r) ps += p0[r];
; #pragma unroll
;     for (int r = 0; r < 16; ++r) ps += p1[r];
;     l_reg += ps;
;     ...
;     PK4(p0, 0, pa0); PK4(p0, 8, pa1); PK4(p1, 0, pa2); PK4(p1, 8, pa3);
.LBB0_140:
	s_andn2_b64 vcc, exec, s[50:51]
	s_cbranch_vccnz .LBB0_137
	s_mul_i32 s42, s65, 0x6000
	v_add_u32_e32 v144, s42, v208
	v_add_u32_e32 v213, v144, v209
	v_add_u32_e32 v214, v144, v210
	v_add_u32_e32 v215, v144, v211
	v_add_u32_e32 v220, v144, v212
	ds_read_b128 v[216:219], v213 offset:32768
	ds_read_b128 v[224:227], v214 offset:32768
	ds_read_b128 v[240:243], v215 offset:32768
	ds_read_b128 v[244:247], v220 offset:32768
	v_readfirstlane_b32 s67, v206
	s_nop 3
	s_cmpk_eq_i32 s66, 0x80
	s_cselect_b32 s66, 0x7f800000, s67
	s_waitcnt lgkmcnt(3)
	v_mfma_f32_32x32x16_bf16 v[80:95], v[216:219], v[96:99], 0
	ds_read_b128 v[216:219], v213 offset:32896
	s_waitcnt lgkmcnt(3)
	v_mfma_f32_32x32x16_bf16 v[80:95], v[224:227], v[100:103], v[80:95]
	ds_read_b128 v[224:227], v214 offset:32896
	s_waitcnt lgkmcnt(3)
	v_mfma_f32_32x32x16_bf16 v[80:95], v[240:243], v[104:107], v[80:95]
	ds_read_b128 v[240:243], v215 offset:32896
	s_waitcnt lgkmcnt(3)
	v_mfma_f32_32x32x16_bf16 v[80:95], v[244:247], v[108:111], v[80:95]
	ds_read_b128 v[244:247], v220 offset:32896
	s_waitcnt lgkmcnt(3)
	v_mfma_f32_32x32x16_bf16 v[80:95], v[216:219], v[112:115], v[80:95]
	ds_read_b128 v[216:219], v213 offset:33024
	s_waitcnt lgkmcnt(3)
	v_mfma_f32_32x32x16_bf16 v[80:95], v[224:227], v[116:119], v[80:95]
	ds_read_b128 v[224:227], v214 offset:33024
	s_waitcnt lgkmcnt(3)
	v_mfma_f32_32x32x16_bf16 v[80:95], v[240:243], v[120:123], v[80:95]
	ds_read_b128 v[240:243], v215 offset:33024
	s_waitcnt lgkmcnt(3)
	v_mfma_f32_32x32x16_bf16 v[80:95], v[244:247], v[124:127], v[80:95]
	ds_read_b128 v[244:247], v220 offset:33024
	s_waitcnt lgkmcnt(3)
	v_mfma_f32_32x32x16_bf16 v[80:95], v[216:219], v[128:131], v[80:95]
	ds_read_b128 v[216:219], v213 offset:45056
	s_waitcnt lgkmcnt(3)
	v_mfma_f32_32x32x16_bf16 v[80:95], v[224:227], v[132:135], v[80:95]
	ds_read_b128 v[224:227], v214 offset:45056
	s_waitcnt lgkmcnt(3)
	v_mfma_f32_32x32x16_bf16 v[80:95], v[240:243], v[136:139], v[80:95]
	ds_read_b128 v[240:243], v215 offset:45056
	s_waitcnt lgkmcnt(3)
	v_mfma_f32_32x32x16_bf16 v[80:95], v[244:247], v[140:143], v[80:95]
	ds_read_b128 v[244:247], v220 offset:45056
	s_waitcnt lgkmcnt(3)
	v_mfma_f32_32x32x16_bf16 v[64:79], v[216:219], v[96:99], 0
	ds_read_b128 v[216:219], v213 offset:45184
	s_waitcnt lgkmcnt(3)
	v_mfma_f32_32x32x16_bf16 v[64:79], v[224:227], v[100:103], v[64:79]
	ds_read_b128 v[224:227], v214 offset:45184
	s_waitcnt lgkmcnt(3)
	v_mfma_f32_32x32x16_bf16 v[64:79], v[240:243], v[104:107], v[64:79]
	ds_read_b128 v[240:243], v215 offset:45184
	s_waitcnt lgkmcnt(3)
	v_mfma_f32_32x32x16_bf16 v[64:79], v[244:247], v[108:111], v[64:79]
	ds_read_b128 v[244:247], v220 offset:45184
	s_cmp_eq_u32 s66, 0
	s_cbranch_scc1 .Latt_fast
	v_subrev_f32_e32 v80, s67, v80
	v_subrev_f32_e32 v81, s67, v81
	v_exp_f32_e32 v80, v80
	v_subrev_f32_e32 v82, s67, v82
	v_exp_f32_e32 v81, v81
	v_subrev_f32_e32 v83, s67, v83
	v_exp_f32_e32 v82, v82
	s_waitcnt lgkmcnt(3)
	v_mfma_f32_32x32x16_bf16 v[64:79], v[216:219], v[112:115], v[64:79]
	ds_read_b128 v[216:219], v213 offset:45312
	v_subrev_f32_e32 v84, s67, v84
	v_exp_f32_e32 v83, v83
	v_add_f32_e32 v146, v80, v81
	v_subrev_f32_e32 v85, s67, v85
	v_exp_f32_e32 v84, v84
	v_add_f32_e32 v146, v82, v146
	v_subrev_f32_e32 v86, s67, v86
	s_waitcnt lgkmcnt(3)
	v_mfma_f32_32x32x16_bf16 v[64:79], v[224:227], v[116:119], v[64:79]
	ds_read_b128 v[224:227], v214 offset:45312
	v_exp_f32_e32 v85, v85
	v_add_f32_e32 v146, v83, v146
	v_subrev_f32_e32 v87, s67, v87
	v_exp_f32_e32 v86, v86
	v_add_f32_e32 v146, v84, v146
	v_subrev_f32_e32 v88, s66, v88
	v_exp_f32_e32 v87, v87
	s_waitcnt lgkmcnt(3)
	v_mfma_f32_32x32x16_bf16 v[64:79], v[240:243], v[120:123], v[64:79]
	ds_read_b128 v[240:243], v215 offset:45312
	v_add_f32_e32 v146, v85, v146
	v_subrev_f32_e32 v89, s66, v89
	v_exp_f32_e32 v88, v88
	v_add_f32_e32 v146, v86, v146
	v_subrev_f32_e32 v90, s66, v90
	v_exp_f32_e32 v89, v89
	v_add_f32_e32 v146, v87, v146
	s_waitcnt lgkmcnt(3)
	v_mfma_f32_32x32x16_bf16 v[64:79], v[244:247], v[124:127], v[64:79]
	v_lshl_add_u32 v147, s65, 14, v221
	ds_read_b128 v[244:247], v220 offset:45312
	v_subrev_f32_e32 v91, s66, v91
	v_exp_f32_e32 v90, v90
	v_add_f32_e32 v146, v88, v146
	v_subrev_f32_e32 v92, s66, v92
	v_exp_f32_e32 v91, v91
	v_add_f32_e32 v146, v89, v146
	v_subrev_f32_e32 v93, s66, v93
	s_waitcnt lgkmcnt(3)
	v_mfma_f32_32x32x16_bf16 v[64:79], v[216:219], v[128:131], v[64:79]
	ds_read_b64_tr_b16 v[216:217], v147 offset:0
	ds_read_b64_tr_b16 v[218:219], v147 offset:2048
	v_exp_f32_e32 v92, v92
	v_add_f32_e32 v146, v90, v146
	v_subrev_f32_e32 v94, s66, v94
	v_exp_f32_e32 v93, v93
	v_add_f32_e32 v146, v91, v146
	v_subrev_f32_e32 v95, s66, v95
	v_exp_f32_e32 v94, v94
	s_waitcnt lgkmcnt(4)
	v_mfma_f32_32x32x16_bf16 v[64:79], v[224:227], v[132:135], v[64:79]
	ds_read_b64_tr_b16 v[224:225], v147 offset:4096
	ds_read_b64_tr_b16 v[226:227], v147 offset:6144
	v_add_f32_e32 v146, v92, v146
	v_exp_f32_e32 v95, v95
	v_add_f32_e32 v146, v93, v146
	v_add_f32_e32 v146, v94, v146
	v_add_f32_e32 v146, v95, v146
	v_cvt_pk_bf16_f32 v80, v80, v81
	v_cvt_pk_bf16_f32 v81, v82, v83
	s_waitcnt lgkmcnt(5)
	v_mfma_f32_32x32x16_bf16 v[64:79], v[240:243], v[136:139], v[64:79]
	ds_read_b64_tr_b16 v[240:241], v147 offset:512
	ds_read_b64_tr_b16 v[242:243], v147 offset:2560
	v_cvt_pk_bf16_f32 v82, v84, v85
	v_cvt_pk_bf16_f32 v83, v86, v87
	v_cvt_pk_bf16_f32 v84, v88, v89
	v_cvt_pk_bf16_f32 v85, v90, v91
	v_cvt_pk_bf16_f32 v86, v92, v93
	v_cvt_pk_bf16_f32 v87, v94, v95
	v_permlane32_swap_b32_e32 v80, v82
	s_waitcnt lgkmcnt(6)
; #define SBAR() __builtin_amdgcn_sched_barrier(0)
; __device__ __forceinline__ void pv_d0(f32x16* o, int vb, bf16x8 pa0, bf16x8 pa1, bf16x8 pa2, bf16x8 pa3) {
;     VBlk A, B;
;     pv_load<0>(A, vb); pv_load<1>(B, vb);
;     asm volatile("s_waitcnt lgkmcnt(8)" ::: "memory"); SBAR(); pv_mma(o[0], A, pa0, pa1, pa2, pa3); SBAR();
;     pv_load<2>(A, vb);
;     asm volatile("s_waitcnt lgkmcnt(8)" ::: "memory"); SBAR(); pv_mma(o[1], B, pa0, pa1, pa2, pa3); SBAR();
;     pv_load<3>(B, vb);
;     asm volatile("s_waitcnt lgkmcnt(8)" ::: "memory"); SBAR(); pv_mma(o[2], A, pa0, pa1, pa2, pa3); SBAR();
;     asm volatile("s_waitcnt lgkmcnt(0)" ::: "memory"); SBAR(); pv_mma(o[3], B, pa0, pa1, pa2, pa3); SBAR();
; }
; __device__ __forceinline__ void finishP(const f32x16& p0, const f32x16& p1, float& l_reg, bf16x8& pa0, bf16x8& pa1, bf16x8& pa2, bf16x8& pa3) {
;     float ps = 0.f;
; #pragma unroll
;     for (int r = 0; r < 16; ++r) ps += p0[r];
; #pragma unroll
;     for (int r = 0; r < 16; ++r) ps += p1[r];
;     l_reg += ps;
;     ...
;     PK4(p0, 0, pa0); PK4(p0, 8, pa1); PK4(p1, 0, pa2); PK4(p1, 8, pa3);
	v_mfma_f32_32x32x16_bf16 v[64:79], v[244:247], v[140:143], v[64:79]
	ds_read_b64_tr_b16 v[244:245], v147 offset:4608
	ds_read_b64_tr_b16 v[246:247], v147 offset:6656
	v_permlane32_swap_b32_e32 v81, v83
	v_permlane32_swap_b32_e32 v84, v86
	v_permlane32_swap_b32_e32 v85, v87
	ds_read_b64_tr_b16 v[88:89], v147 offset:1024
	ds_read_b64_tr_b16 v[90:91], v147 offset:3072
	ds_read_b64_tr_b16 v[92:93], v147 offset:5120
	ds_read_b64_tr_b16 v[94:95], v147 offset:7168
	s_waitcnt lgkmcnt(10)
	v_mfma_f32_32x32x16_bf16 v[48:63], v[80:83], v[216:219], v[48:63]
	ds_read_b64_tr_b16 v[216:217], v147 offset:1536
	ds_read_b64_tr_b16 v[218:219], v147 offset:3584
	v_subrev_f32_e32 v64, s66, v64
	v_subrev_f32_e32 v65, s66, v65
	v_exp_f32_e32 v64, v64
	v_subrev_f32_e32 v66, s66, v66
	v_exp_f32_e32 v65, v65
	v_subrev_f32_e32 v67, s66, v67
	v_exp_f32_e32 v66, v66
	v_add_f32_e32 v146, v64, v146
	s_waitcnt lgkmcnt(10)
	v_mfma_f32_32x32x16_bf16 v[48:63], v[84:87], v[224:227], v[48:63]
	ds_read_b64_tr_b16 v[224:225], v147 offset:5632
	ds_read_b64_tr_b16 v[226:227], v147 offset:7680
	v_subrev_f32_e32 v68, s66, v68
	v_exp_f32_e32 v67, v67
	v_add_f32_e32 v146, v65, v146
	v_subrev_f32_e32 v69, s66, v69
	v_exp_f32_e32 v68, v68
	v_add_f32_e32 v146, v66, v146
	v_subrev_f32_e32 v70, s66, v70
	v_exp_f32_e32 v69, v69
	s_waitcnt lgkmcnt(10)
	v_mfma_f32_32x32x16_bf16 v[32:47], v[80:83], v[240:243], v[32:47]
	ds_read_b64_tr_b16 v[240:241], v147 offset:8192
	ds_read_b64_tr_b16 v[242:243], v147 offset:10240
	v_add_f32_e32 v146, v67, v146
	v_subrev_f32_e32 v71, s66, v71
	v_exp_f32_e32 v70, v70
	v_add_f32_e32 v146, v68, v146
	v_subrev_f32_e32 v72, s66, v72
	v_exp_f32_e32 v71, v71
	v_add_f32_e32 v146, v69, v146
	v_subrev_f32_e32 v73, s66, v73
	s_waitcnt lgkmcnt(10)
	v_mfma_f32_32x32x16_bf16 v[32:47], v[84:87], v[244:247], v[32:47]
	ds_read_b64_tr_b16 v[244:245], v147 offset:12288
	ds_read_b64_tr_b16 v[246:247], v147 offset:14336
	v_exp_f32_e32 v72, v72
	v_add_f32_e32 v146, v70, v146
	v_subrev_f32_e32 v74, s66, v74
	v_exp_f32_e32 v73, v73
	v_add_f32_e32 v146, v71, v146
	v_subrev_f32_e32 v75, s66, v75
	v_exp_f32_e32 v74, v74
	v_add_f32_e32 v146, v72, v146
	s_waitcnt lgkmcnt(10)
	v_mfma_f32_32x32x16_bf16 v[16:31], v[80:83], v[88:91], v[16:31]
	ds_read_b64_tr_b16 v[88:89], v147 offset:8704
	ds_read_b64_tr_b16 v[90:91], v147 offset:10752
	v_subrev_f32_e32 v76, s66, v76
	v_exp_f32_e32 v75, v75
	v_add_f32_e32 v146, v73, v146
	v_subrev_f32_e32 v77, s66, v77
	v_exp_f32_e32 v76, v76
	v_add_f32_e32 v146, v74, v146
	v_subrev_f32_e32 v78, s66, v78
	v_exp_f32_e32 v77, v77
	s_waitcnt lgkmcnt(10)
	v_mfma_f32_32x32x16_bf16 v[16:31], v[84:87], v[92:95], v[16:31]
	ds_read_b64_tr_b16 v[92:93], v147 offset:12800
	ds_read_b64_tr_b16 v[94:95], v147 offset:14848
	v_add_f32_e32 v146, v75, v146
	v_subrev_f32_e32 v79, s66, v79
	v_exp_f32_e32 v78, v78
	v_add_f32_e32 v146, v76, v146
	v_exp_f32_e32 v79, v79
	v_add_f32_e32 v146, v77, v146
	v_add_f32_e32 v146, v78, v146
	v_add_f32_e32 v146, v79, v146
	s_waitcnt lgkmcnt(10)
	v_mfma_f32_32x32x16_bf16 v[0:15], v[80:83], v[216:219], v[0:15]
	ds_read_b64_tr_b16 v[216:217], v147 offset:9216
	ds_read_b64_tr_b16 v[218:219], v147 offset:11264
	v_cvt_pk_bf16_f32 v64, v64, v65
	v_cvt_pk_bf16_f32 v65, v66, v67
	v_cvt_pk_bf16_f32 v66, v68, v69
	v_cvt_pk_bf16_f32 v67, v70, v71
	v_cvt_pk_bf16_f32 v68, v72, v73
	v_cvt_pk_bf16_f32 v69, v74, v75
	v_cvt_pk_bf16_f32 v70, v76, v77
	v_cvt_pk_bf16_f32 v71, v78, v79
	s_waitcnt lgkmcnt(10)
	v_mfma_f32_32x32x16_bf16 v[0:15], v[84:87], v[224:227], v[0:15]
	ds_read_b64_tr_b16 v[224:225], v147 offset:13312
	ds_read_b64_tr_b16 v[226:227], v147 offset:15360
	v_permlane32_swap_b32_e32 v64, v66
	v_permlane32_swap_b32_e32 v65, v67
	v_permlane32_swap_b32_e32 v68, v70
	v_permlane32_swap_b32_e32 v69, v71
	v_add_f32_e32 v155, v155, v146
	ds_read_b64_tr_b16 v[72:73], v147 offset:9728
	ds_read_b64_tr_b16 v[74:75], v147 offset:11776
	s_waitcnt lgkmcnt(12)
	v_mfma_f32_32x32x16_bf16 v[48:63], v[64:67], v[240:243], v[48:63]
	ds_read_b64_tr_b16 v[76:77], v147 offset:13824
	ds_read_b64_tr_b16 v[78:79], v147 offset:15872
	s_waitcnt lgkmcnt(12)
	v_mfma_f32_32x32x16_bf16 v[48:63], v[68:71], v[244:247], v[48:63]
	s_waitcnt lgkmcnt(10)
	v_mfma_f32_32x32x16_bf16 v[32:47], v[64:67], v[88:91], v[32:47]
	s_waitcnt lgkmcnt(8)
	v_mfma_f32_32x32x16_bf16 v[32:47], v[68:71], v[92:95], v[32:47]
	s_waitcnt lgkmcnt(6)
	v_mfma_f32_32x32x16_bf16 v[16:31], v[64:67], v[216:219], v[16:31]
	s_waitcnt lgkmcnt(4)
	v_mfma_f32_32x32x16_bf16 v[16:31], v[68:71], v[224:227], v[16:31]
	s_waitcnt lgkmcnt(2)
	v_mfma_f32_32x32x16_bf16 v[0:15], v[64:67], v[72:75], v[0:15]
	s_waitcnt lgkmcnt(0)
	v_mfma_f32_32x32x16_bf16 v[0:15], v[68:71], v[76:79], v[0:15]
	s_branch .LBB0_137
; #define SBAR() __builtin_amdgcn_sched_barrier(0)
; __device__ __forceinline__ void pv_d0(f32x16* o, int vb, bf16x8 pa0, bf16x8 pa1, bf16x8 pa2, bf16x8 pa3) {
;     VBlk A, B;
;     pv_load<0>(A, vb); pv_load<1>(B, vb);
;     asm volatile("s_waitcnt lgkmcnt(8)" ::: "memory"); SBAR(); pv_mma(o[0], A, pa0, pa1, pa2, pa3); SBAR();
;     pv_load<2>(A, vb);
;     asm volatile("s_waitcnt lgkmcnt(8)" ::: "memory"); SBAR(); pv_mma(o[1], B, pa0, pa1, pa2, pa3); SBAR();
;     pv_load<3>(B, vb);
;     asm volatile("s_waitcnt lgkmcnt(8)" ::: "memory"); SBAR(); pv_mma(o[2], A, pa0, pa1, pa2, pa3); SBAR();
;     asm volatile("s_waitcnt lgkmcnt(0)" ::: "memory"); SBAR(); pv_mma(o[3], B, pa0, pa1, pa2, pa3); SBAR();
; }
; __device__ __forceinline__ void expP(f32x16& p0, f32x16& p1, float MB) {
; #pragma unroll
;     for (int r = 0; r < 16; ++r) p0[r] = __builtin_amdgcn_exp2f(p0[r] - MB);
; #pragma unroll
;     for (int r = 0; r < 16; ++r) p1[r] = __builtin_amdgcn_exp2f(p1[r] - MB);
; }
; __device__ __forceinline__ void maskLast(f32x16& p0, f32x16& p1) {
; #pragma unroll
;     for (int r = 8; r < 16; ++r) p0[r] = 0.f;
; #pragma unroll
;     for (int r = 0; r < 16; ++r) p1[r] = 0.f;
; }
; __device__ __forceinline__ void finishP(const f32x16& p0, const f32x16& p1, float& l_reg, bf16x8& pa0, bf16x8& pa1, bf16x8& pa2, bf16x8& pa3) {
;     float ps = 0.f;
; #pragma unroll
;     for (int r = 0; r < 16; ++r) ps += p0[r];
; #pragma unroll
;     for (int r = 0; r < 16; ++r) ps += p1[r];
;     l_reg += ps;
;     ...
;     PK4(p0, 0, pa0); PK4(p0, 8, pa1); PK4(p1, 0, pa2); PK4(p1, 8, pa3);
.Latt_fast:
	v_exp_f32_e32 v80, v80
	v_exp_f32_e32 v81, v81
	v_exp_f32_e32 v82, v82
	v_exp_f32_e32 v83, v83
	v_add_f32_e32 v146, v80, v81
	v_exp_f32_e32 v84, v84
	v_add_f32_e32 v146, v82, v146
	s_waitcnt lgkmcnt(3)
	v_mfma_f32_32x32x16_bf16 v[64:79], v[216:219], v[112:115], v[64:79]
	ds_read_b128 v[216:219], v213 offset:45312
	v_exp_f32_e32 v85, v85
	v_add_f32_e32 v146, v83, v146
	v_exp_f32_e32 v86, v86
	v_add_f32_e32 v146, v84, v146
	v_exp_f32_e32 v87, v87
	v_add_f32_e32 v146, v85, v146
	v_exp_f32_e32 v88, v88
	s_waitcnt lgkmcnt(3)
	v_mfma_f32_32x32x16_bf16 v[64:79], v[224:227], v[116:119], v[64:79]
	ds_read_b128 v[224:227], v214 offset:45312
	v_add_f32_e32 v146, v86, v146
	v_exp_f32_e32 v89, v89
	v_add_f32_e32 v146, v87, v146
	v_exp_f32_e32 v90, v90
	v_add_f32_e32 v146, v88, v146
	v_exp_f32_e32 v91, v91
	v_add_f32_e32 v146, v89, v146
	s_waitcnt lgkmcnt(3)
	v_mfma_f32_32x32x16_bf16 v[64:79], v[240:243], v[120:123], v[64:79]
	ds_read_b128 v[240:243], v215 offset:45312
	v_exp_f32_e32 v92, v92
	v_add_f32_e32 v146, v90, v146
	v_exp_f32_e32 v93, v93
	v_add_f32_e32 v146, v91, v146
	v_exp_f32_e32 v94, v94
	v_add_f32_e32 v146, v92, v146
	v_exp_f32_e32 v95, v95
	s_waitcnt lgkmcnt(3)
	v_mfma_f32_32x32x16_bf16 v[64:79], v[244:247], v[124:127], v[64:79]
	v_lshl_add_u32 v147, s65, 14, v221
	ds_read_b128 v[244:247], v220 offset:45312
	v_add_f32_e32 v146, v93, v146
	v_add_f32_e32 v146, v94, v146
	v_add_f32_e32 v146, v95, v146
	v_cvt_pk_bf16_f32 v80, v80, v81
	v_cvt_pk_bf16_f32 v81, v82, v83
	v_cvt_pk_bf16_f32 v82, v84, v85
	v_cvt_pk_bf16_f32 v83, v86, v87
	s_waitcnt lgkmcnt(3)
	v_mfma_f32_32x32x16_bf16 v[64:79], v[216:219], v[128:131], v[64:79]
	ds_read_b64_tr_b16 v[216:217], v147 offset:0
	ds_read_b64_tr_b16 v[218:219], v147 offset:2048
	v_cvt_pk_bf16_f32 v84, v88, v89
	v_cvt_pk_bf16_f32 v85, v90, v91
	v_cvt_pk_bf16_f32 v86, v92, v93
	v_cvt_pk_bf16_f32 v87, v94, v95
	v_permlane32_swap_b32_e32 v80, v82
	v_permlane32_swap_b32_e32 v81, v83
	v_permlane32_swap_b32_e32 v84, v86
	s_waitcnt lgkmcnt(4)
	v_mfma_f32_32x32x16_bf16 v[64:79], v[224:227], v[132:135], v[64:79]
	ds_read_b64_tr_b16 v[224:225], v147 offset:4096
	ds_read_b64_tr_b16 v[226:227], v147 offset:6144
	v_permlane32_swap_b32_e32 v85, v87
	ds_read_b64_tr_b16 v[88:89], v147 offset:512
	ds_read_b64_tr_b16 v[90:91], v147 offset:2560
	ds_read_b64_tr_b16 v[92:93], v147 offset:4608
	ds_read_b64_tr_b16 v[94:95], v147 offset:6656
	s_waitcnt lgkmcnt(9)
	v_mfma_f32_32x32x16_bf16 v[64:79], v[240:243], v[136:139], v[64:79]
	ds_read_b64_tr_b16 v[240:241], v147 offset:1024
	ds_read_b64_tr_b16 v[242:243], v147 offset:3072
	s_waitcnt lgkmcnt(10)
	v_mfma_f32_32x32x16_bf16 v[64:79], v[244:247], v[140:143], v[64:79]
	ds_read_b64_tr_b16 v[244:245], v147 offset:5120
	ds_read_b64_tr_b16 v[246:247], v147 offset:7168
	s_waitcnt lgkmcnt(10)
	v_mfma_f32_32x32x16_bf16 v[48:63], v[80:83], v[216:219], v[48:63]
	ds_read_b64_tr_b16 v[216:217], v147 offset:1536
	ds_read_b64_tr_b16 v[218:219], v147 offset:3584
	s_waitcnt lgkmcnt(10)
	v_mfma_f32_32x32x16_bf16 v[48:63], v[84:87], v[224:227], v[48:63]
	ds_read_b64_tr_b16 v[224:225], v147 offset:5632
	ds_read_b64_tr_b16 v[226:227], v147 offset:7680
	s_waitcnt lgkmcnt(10)
	v_mfma_f32_32x32x16_bf16 v[32:47], v[80:83], v[88:91], v[32:47]
	ds_read_b64_tr_b16 v[88:89], v147 offset:8192
	ds_read_b64_tr_b16 v[90:91], v147 offset:10240
	v_exp_f32_e32 v64, v64
	v_exp_f32_e32 v65, v65
	v_exp_f32_e32 v66, v66
	v_add_f32_e32 v146, v64, v146
	v_exp_f32_e32 v67, v67
	v_add_f32_e32 v146, v65, v146
	v_exp_f32_e32 v68, v68
	v_add_f32_e32 v146, v66, v146
	s_waitcnt lgkmcnt(10)
	v_mfma_f32_32x32x16_bf16 v[32:47], v[84:87], v[92:95], v[32:47]
	ds_read_b64_tr_b16 v[92:93], v147 offset:12288
	ds_read_b64_tr_b16 v[94:95], v147 offset:14336
	v_exp_f32_e32 v69, v69
	v_add_f32_e32 v146, v67, v146
	v_exp_f32_e32 v70, v70
	v_add_f32_e32 v146, v68, v146
	v_exp_f32_e32 v71, v71
	v_add_f32_e32 v146, v69, v146
	v_exp_f32_e32 v72, v72
	v_add_f32_e32 v146, v70, v146
	s_waitcnt lgkmcnt(10)
	v_mfma_f32_32x32x16_bf16 v[16:31], v[80:83], v[240:243], v[16:31]
	ds_read_b64_tr_b16 v[240:241], v147 offset:8704
	ds_read_b64_tr_b16 v[242:243], v147 offset:10752
	v_exp_f32_e32 v73, v73
	v_add_f32_e32 v146, v71, v146
	v_exp_f32_e32 v74, v74
	v_add_f32_e32 v146, v72, v146
	v_exp_f32_e32 v75, v75
	v_add_f32_e32 v146, v73, v146
	v_exp_f32_e32 v76, v76
	v_add_f32_e32 v146, v74, v146
	s_waitcnt lgkmcnt(10)
	v_mfma_f32_32x32x16_bf16 v[16:31], v[84:87], v[244:247], v[16:31]
	ds_read_b64_tr_b16 v[244:245], v147 offset:12800
	ds_read_b64_tr_b16 v[246:247], v147 offset:14848
	v_exp_f32_e32 v77, v77
	v_add_f32_e32 v146, v75, v146
	v_exp_f32_e32 v78, v78
	v_add_f32_e32 v146, v76, v146
	v_exp_f32_e32 v79, v79
	v_add_f32_e32 v146, v77, v146
	v_add_f32_e32 v146, v78, v146
	v_add_f32_e32 v146, v79, v146
	s_waitcnt lgkmcnt(10)
	v_mfma_f32_32x32x16_bf16 v[0:15], v[80:83], v[216:219], v[0:15]
	ds_read_b64_tr_b16 v[216:217], v147 offset:9216
	ds_read_b64_tr_b16 v[218:219], v147 offset:11264
	v_cvt_pk_bf16_f32 v64, v64, v65
	v_cvt_pk_bf16_f32 v65, v66, v67
	v_cvt_pk_bf16_f32 v66, v68, v69
	v_cvt_pk_bf16_f32 v67, v70, v71
	v_cvt_pk_bf16_f32 v68, v72, v73
	v_cvt_pk_bf16_f32 v69, v74, v75
	v_cvt_pk_bf16_f32 v70, v76, v77
	v_cvt_pk_bf16_f32 v71, v78, v79
	s_waitcnt lgkmcnt(10)
	v_mfma_f32_32x32x16_bf16 v[0:15], v[84:87], v[224:227], v[0:15]
	ds_read_b64_tr_b16 v[224:225], v147 offset:13312
	ds_read_b64_tr_b16 v[226:227], v147 offset:15360
	v_permlane32_swap_b32_e32 v64, v66
	v_permlane32_swap_b32_e32 v65, v67
	v_permlane32_swap_b32_e32 v68, v70
	v_permlane32_swap_b32_e32 v69, v71
	v_add_f32_e32 v155, v155, v146
	ds_read_b64_tr_b16 v[72:73], v147 offset:9728
	ds_read_b64_tr_b16 v[74:75], v147 offset:11776
	s_waitcnt lgkmcnt(12)
	v_mfma_f32_32x32x16_bf16 v[48:63], v[64:67], v[88:91], v[48:63]
	ds_read_b64_tr_b16 v[76:77], v147 offset:13824
	ds_read_b64_tr_b16 v[78:79], v147 offset:15872
	s_waitcnt lgkmcnt(12)
	v_mfma_f32_32x32x16_bf16 v[48:63], v[68:71], v[92:95], v[48:63]
	s_waitcnt lgkmcnt(10)
	v_mfma_f32_32x32x16_bf16 v[32:47], v[64:67], v[240:243], v[32:47]
	s_waitcnt lgkmcnt(8)
	v_mfma_f32_32x32x16_bf16 v[32:47], v[68:71], v[244:247], v[32:47]
	s_waitcnt lgkmcnt(6)
	v_mfma_f32_32x32x16_bf16 v[16:31], v[64:67], v[216:219], v[16:31]
	s_waitcnt lgkmcnt(4)
	v_mfma_f32_32x32x16_bf16 v[16:31], v[68:71], v[224:227], v[16:31]
	s_waitcnt lgkmcnt(2)
	v_mfma_f32_32x32x16_bf16 v[0:15], v[64:67], v[72:75], v[0:15]
	s_waitcnt lgkmcnt(0)
	v_mfma_f32_32x32x16_bf16 v[0:15], v[68:71], v[76:79], v[0:15]
	s_branch .LBB0_137
